# v9_backedge_hoist_plus_wt_p3p6p7
# speedup vs baseline: 1.0525x; 1.0008x over previous
.LBB0_546:
	s_or_b64 exec, exec, s[0:1]
	s_waitcnt lgkmcnt(0)
	ds_read_b128 v[32:35], v215 offset:128
	ds_read_b128 v[36:39], v215 offset:160
	s_lshl_b64 s[0:1], s[56:57], 24
	v_readlane_b32 s8, v246, 45
	s_add_u32 s8, s8, s0
	v_readlane_b32 s9, v246, 46
	s_waitcnt lgkmcnt(1)
	v_rcp_f32_e32 v40, v32
	s_addc_u32 s9, s9, s1
	s_add_u32 s44, s8, s58
	v_rcp_f32_e32 v41, v33
	s_addc_u32 s45, s9, s59
	v_readlane_b32 s8, v246, 47
	s_add_u32 s0, s8, s0
	v_mul_f32_e32 v0, v0, v40
	v_cvt_pk_bf16_f32 v0, v0, s0
	v_rcp_f32_e32 v42, v34
	ds_write_b16 v217, v0 offset:64
	v_mul_f32_e32 v0, v17, v41
	v_cvt_pk_bf16_f32 v0, v0, s0
	ds_write_b16 v217, v0 offset:128
	v_mul_f32_e32 v0, v1, v41
	v_cvt_pk_bf16_f32 v0, v0, s0
	v_rcp_f32_e32 v43, v35
	ds_write_b16 v217, v0 offset:192
	v_mul_f32_e32 v0, v18, v42
	v_cvt_pk_bf16_f32 v0, v0, s0
	ds_write_b16 v217, v0 offset:256
	v_mul_f32_e32 v0, v2, v42
	v_cvt_pk_bf16_f32 v0, v0, s0
	s_waitcnt lgkmcnt(4)
	v_rcp_f32_e32 v44, v36
	ds_write_b16 v217, v0 offset:320
	v_mul_f32_e32 v0, v19, v43
	v_cvt_pk_bf16_f32 v0, v0, s0
	ds_write_b16 v217, v0 offset:384
	v_mul_f32_e32 v0, v3, v43
	v_cvt_pk_bf16_f32 v0, v0, s0
	v_rcp_f32_e32 v45, v37
	ds_write_b16 v217, v0 offset:448
	v_mul_f32_e32 v0, v20, v44
	v_cvt_pk_bf16_f32 v0, v0, s0
	ds_write_b16 v217, v0 offset:1024
	v_mul_f32_e32 v0, v4, v44
	v_cvt_pk_bf16_f32 v0, v0, s0
	v_rcp_f32_e32 v46, v38
	ds_write_b16 v217, v0 offset:1088
	v_mul_f32_e32 v0, v21, v45
	v_cvt_pk_bf16_f32 v0, v0, s0
	ds_write_b16 v217, v0 offset:1152
	v_mul_f32_e32 v0, v5, v45
	ds_read_b128 v[32:35], v215 offset:192
	v_cvt_pk_bf16_f32 v0, v0, s0
	v_rcp_f32_e32 v47, v39
	ds_write_b16 v217, v0 offset:1216
	v_mul_f32_e32 v0, v22, v46
	v_cvt_pk_bf16_f32 v0, v0, s0
	ds_write_b16 v217, v0 offset:1280
	v_mul_f32_e32 v0, v6, v46
	v_cvt_pk_bf16_f32 v0, v0, s0
	ds_read_b128 v[36:39], v215 offset:224
	s_waitcnt lgkmcnt(3)
	v_rcp_f32_e32 v32, v32
	ds_write_b16 v217, v0 offset:1344
	v_mul_f32_e32 v0, v23, v47
	v_cvt_pk_bf16_f32 v0, v0, s0
	ds_write_b16 v217, v0 offset:1408
	v_mul_f32_e32 v0, v7, v47
	v_cvt_pk_bf16_f32 v0, v0, s0
	v_rcp_f32_e32 v33, v33
	ds_write_b16 v217, v0 offset:1472
	v_mul_f32_e32 v0, v24, v32
	v_cvt_pk_bf16_f32 v0, v0, s0
	ds_write_b16 v217, v0 offset:2048
	v_mul_f32_e32 v0, v8, v32
	v_cvt_pk_bf16_f32 v0, v0, s0
	v_rcp_f32_e32 v34, v34
	ds_write_b16 v217, v0 offset:2112
	v_mul_f32_e32 v0, v25, v33
	v_cvt_pk_bf16_f32 v0, v0, s0
	ds_write_b16 v217, v0 offset:2176
	v_mul_f32_e32 v0, v9, v33
	v_cvt_pk_bf16_f32 v0, v0, s0
	v_rcp_f32_e32 v35, v35
	ds_write_b16 v217, v0 offset:2240
	v_mul_f32_e32 v0, v26, v34
	v_cvt_pk_bf16_f32 v0, v0, s0
	ds_write_b16 v217, v0 offset:2304
	v_mul_f32_e32 v0, v10, v34
	v_cvt_pk_bf16_f32 v0, v0, s0
	s_waitcnt lgkmcnt(8)
	v_rcp_f32_e32 v36, v36
	ds_write_b16 v217, v0 offset:2368
	v_mul_f32_e32 v0, v27, v35
	v_cvt_pk_bf16_f32 v0, v0, s0
	ds_write_b16 v217, v0 offset:2432
	v_mul_f32_e32 v0, v11, v35
	v_cvt_pk_bf16_f32 v0, v0, s0
	v_rcp_f32_e32 v37, v37
	ds_write_b16 v217, v0 offset:2496
	v_mul_f32_e32 v0, v28, v36
	v_cvt_pk_bf16_f32 v0, v0, s0
	ds_write_b16 v217, v0 offset:3072
	v_mul_f32_e32 v0, v12, v36
	v_cvt_pk_bf16_f32 v0, v0, s0
	v_rcp_f32_e32 v38, v38
	ds_write_b16 v217, v0 offset:3136
	v_mul_f32_e32 v0, v29, v37
	v_cvt_pk_bf16_f32 v0, v0, s0
	ds_write_b16 v217, v0 offset:3200
	v_mul_f32_e32 v0, v13, v37
	v_cvt_pk_bf16_f32 v0, v0, s0
	v_rcp_f32_e32 v39, v39
	ds_write_b16 v217, v0 offset:3264
	v_mul_f32_e32 v0, v30, v38
	v_cvt_pk_bf16_f32 v0, v0, s0
	ds_write_b16 v217, v0 offset:3328
	v_mul_f32_e32 v0, v14, v38
	v_cvt_pk_bf16_f32 v0, v0, s0
	v_readlane_b32 s8, v246, 48
	ds_write_b16 v217, v0 offset:3392
	v_mul_f32_e32 v0, v31, v39
	s_addc_u32 s1, s8, s1
	v_cvt_pk_bf16_f32 v0, v0, s0
	s_add_u32 s8, s0, s58
	v_mul_f32_e32 v16, v16, v40
	ds_write_b16 v217, v0 offset:3456
	v_mul_f32_e32 v0, v15, v39
	s_addc_u32 s9, s1, s59
	v_cvt_pk_bf16_f32 v16, v16, s0
	v_cvt_pk_bf16_f32 v0, v0, s0
	s_lshl_b64 s[0:1], s[52:53], 11
	s_add_u32 s44, s44, s0
	s_addc_u32 s45, s45, s1
	v_mov_b32_e32 v145, v153
	ds_write_b16 v217, v16
	ds_write_b16 v217, v0 offset:3520
	v_lshl_add_u64 v[16:17], s[44:45], 0, v[144:145]
	v_lshlrev_b64 v[140:141], 1, v[154:155]
	s_waitcnt lgkmcnt(0)
	v_lshl_add_u64 v[0:1], v[16:17], 0, v[140:141]
	global_load_dwordx4 v[0:3], v[0:1], off
	v_lshlrev_b64 v[142:143], 1, v[156:157]
	v_lshl_add_u64 v[4:5], v[16:17], 0, v[142:143]
	global_load_dwordx4 v[4:7], v[4:5], off
	v_lshlrev_b64 v[166:167], 1, v[158:159]
	v_lshl_add_u64 v[8:9], v[16:17], 0, v[166:167]
	global_load_dwordx4 v[8:11], v[8:9], off
	v_lshlrev_b64 v[168:169], 1, v[160:161]
	v_lshl_add_u64 v[16:17], v[16:17], 0, v[168:169]
	global_load_dwordx4 v[16:19], v[16:17], off
	ds_read_b128 v[12:15], v177
	s_add_u32 s0, s8, s0
	s_addc_u32 s1, s9, s1
	v_lshl_add_u64 v[20:21], s[0:1], 0, v[144:145]
	s_add_i32 s78, s78, 1
	s_waitcnt lgkmcnt(0)
	v_lshlrev_b32_e32 v22, 16, v12
	v_and_b32_e32 v23, 0xffff0000, v12
	v_lshlrev_b32_e32 v12, 16, v13
	v_and_b32_e32 v13, 0xffff0000, v13
	s_cmp_eq_u32 s78, 3
	s_waitcnt vmcnt(3)
	v_lshlrev_b32_e32 v24, 16, v0
	v_and_b32_e32 v25, 0xffff0000, v0
	v_pk_mul_f32 v[22:23], v[22:23], v[24:25]
	v_lshlrev_b32_e32 v24, 16, v3
	v_cvt_pk_bf16_f32 v0, v22, v23
	v_lshlrev_b32_e32 v22, 16, v1
	v_and_b32_e32 v23, 0xffff0000, v1
	v_pk_mul_f32 v[12:13], v[12:13], v[22:23]
	v_lshlrev_b32_e32 v22, 16, v2
	v_cvt_pk_bf16_f32 v1, v12, v13
	v_lshlrev_b32_e32 v12, 16, v14
	v_and_b32_e32 v13, 0xffff0000, v14
	v_and_b32_e32 v23, 0xffff0000, v2
	v_pk_mul_f32 v[12:13], v[12:13], v[22:23]
	v_lshlrev_b32_e32 v22, 16, v15
	v_cvt_pk_bf16_f32 v2, v12, v13
	v_and_b32_e32 v23, 0xffff0000, v15
	ds_read_b128 v[12:15], v176
	v_and_b32_e32 v25, 0xffff0000, v3
	v_pk_mul_f32 v[22:23], v[22:23], v[24:25]
	s_nop 0
	v_cvt_pk_bf16_f32 v3, v22, v23
	v_lshl_add_u64 v[22:23], v[20:21], 0, v[140:141]
	global_store_dwordx4 v[22:23], v[0:3], off sc1
	s_waitcnt lgkmcnt(0)
	s_nop 0
	v_lshlrev_b32_e32 v0, 16, v12
	v_and_b32_e32 v1, 0xffff0000, v12
	s_waitcnt vmcnt(3)
	v_lshlrev_b32_e32 v2, 16, v4
	v_and_b32_e32 v3, 0xffff0000, v4
	v_pk_mul_f32 v[0:1], v[0:1], v[2:3]
	v_lshlrev_b32_e32 v2, 16, v13
	v_and_b32_e32 v3, 0xffff0000, v13
	v_lshlrev_b32_e32 v4, 16, v5
	v_and_b32_e32 v5, 0xffff0000, v5
	v_pk_mul_f32 v[2:3], v[2:3], v[4:5]
	v_cvt_pk_bf16_f32 v0, v0, v1
	v_cvt_pk_bf16_f32 v1, v2, v3
	v_lshlrev_b32_e32 v2, 16, v14
	v_and_b32_e32 v3, 0xffff0000, v14
	v_lshlrev_b32_e32 v4, 16, v6
	v_and_b32_e32 v5, 0xffff0000, v6
	v_pk_mul_f32 v[2:3], v[2:3], v[4:5]
	v_lshlrev_b32_e32 v12, 16, v15
	v_and_b32_e32 v13, 0xffff0000, v15
	v_lshlrev_b32_e32 v14, 16, v7
	v_and_b32_e32 v15, 0xffff0000, v7
	ds_read_b128 v[4:7], v175
	v_pk_mul_f32 v[12:13], v[12:13], v[14:15]
	v_cvt_pk_bf16_f32 v2, v2, v3
	v_cvt_pk_bf16_f32 v3, v12, v13
	v_lshl_add_u64 v[12:13], v[20:21], 0, v[142:143]
	global_store_dwordx4 v[12:13], v[0:3], off sc1
	s_waitcnt lgkmcnt(0)
	s_nop 0
	v_lshlrev_b32_e32 v0, 16, v4
	v_and_b32_e32 v1, 0xffff0000, v4
	s_waitcnt vmcnt(3)
	v_lshlrev_b32_e32 v2, 16, v8
	v_and_b32_e32 v3, 0xffff0000, v8
	v_pk_mul_f32 v[0:1], v[0:1], v[2:3]
	v_lshlrev_b32_e32 v2, 16, v5
	v_and_b32_e32 v3, 0xffff0000, v5
	v_lshlrev_b32_e32 v4, 16, v9
	v_and_b32_e32 v5, 0xffff0000, v9
	v_pk_mul_f32 v[2:3], v[2:3], v[4:5]
	v_cvt_pk_bf16_f32 v0, v0, v1
	v_cvt_pk_bf16_f32 v1, v2, v3
	v_lshlrev_b32_e32 v2, 16, v6
	v_and_b32_e32 v3, 0xffff0000, v6
	v_lshlrev_b32_e32 v4, 16, v10
	v_and_b32_e32 v5, 0xffff0000, v10
	v_pk_mul_f32 v[2:3], v[2:3], v[4:5]
	v_lshlrev_b32_e32 v8, 16, v7
	v_and_b32_e32 v9, 0xffff0000, v7
	ds_read_b128 v[4:7], v174
	v_lshlrev_b32_e32 v10, 16, v11
	v_and_b32_e32 v11, 0xffff0000, v11
	v_pk_mul_f32 v[8:9], v[8:9], v[10:11]
	v_cvt_pk_bf16_f32 v2, v2, v3
	v_cvt_pk_bf16_f32 v3, v8, v9
	v_lshl_add_u64 v[8:9], v[20:21], 0, v[166:167]
	global_store_dwordx4 v[8:9], v[0:3], off sc1
	s_waitcnt lgkmcnt(0)
	s_nop 0
	v_lshlrev_b32_e32 v0, 16, v4
	v_and_b32_e32 v1, 0xffff0000, v4
	s_waitcnt vmcnt(3)
	v_lshlrev_b32_e32 v2, 16, v16
	v_and_b32_e32 v3, 0xffff0000, v16
	v_pk_mul_f32 v[0:1], v[0:1], v[2:3]
	v_lshlrev_b32_e32 v2, 16, v5
	v_and_b32_e32 v3, 0xffff0000, v5
	v_lshlrev_b32_e32 v4, 16, v17
	v_and_b32_e32 v5, 0xffff0000, v17
	v_pk_mul_f32 v[2:3], v[2:3], v[4:5]
	v_cvt_pk_bf16_f32 v0, v0, v1
	v_cvt_pk_bf16_f32 v1, v2, v3
	v_lshlrev_b32_e32 v2, 16, v6
	v_and_b32_e32 v3, 0xffff0000, v6
	v_lshlrev_b32_e32 v4, 16, v18
	v_and_b32_e32 v5, 0xffff0000, v18
	v_pk_mul_f32 v[2:3], v[2:3], v[4:5]
	v_lshlrev_b32_e32 v4, 16, v7
	v_and_b32_e32 v5, 0xffff0000, v7
	v_lshlrev_b32_e32 v6, 16, v19
	v_and_b32_e32 v7, 0xffff0000, v19
	v_pk_mul_f32 v[4:5], v[4:5], v[6:7]
	v_cvt_pk_bf16_f32 v2, v2, v3
	v_cvt_pk_bf16_f32 v3, v4, v5
	v_lshl_add_u64 v[4:5], v[20:21], 0, v[168:169]
	global_store_dwordx4 v[4:5], v[0:3], off sc1
	s_waitcnt lgkmcnt(0)
	s_barrier
	s_cbranch_scc1 .LBB0_668

.Lstg_mid2:
	s_add_i32 s0, s83, 0x3000
	s_cmpk_lg_u32 s83, 0x9000
	s_cselect_b32 s82, s0, 0
	ds_read_b64_tr_b16 v[72:73], v141 offset:54272
	ds_read_b64_tr_b16 v[74:75], v141 offset:54784
	s_waitcnt lgkmcnt(6)
	v_mfma_f32_32x32x16_bf16 v[16:31], v[132:135], v[64:67], v[16:31]
	v_exp_f32_e32 v48, v48
	v_exp_f32_e32 v49, v49
	v_exp_f32_e32 v50, v50
	v_exp_f32_e32 v51, v51
	ds_read_b64_tr_b16 v[64:65], v141 offset:51200
	ds_read_b64_tr_b16 v[66:67], v141 offset:51712
	s_waitcnt lgkmcnt(6)
	v_mfma_f32_32x32x16_bf16 v[0:15], v[132:135], v[80:83], v[0:15]
	v_exp_f32_e32 v52, v52
	v_exp_f32_e32 v53, v53
	v_exp_f32_e32 v54, v54
	v_exp_f32_e32 v55, v55
	s_add_i32 s0, s79, 0x2000
	s_cmpk_lg_i32 s79, 0x4000
	s_cselect_b32 s0, s0, 0xe800
	s_cmpk_lg_u32 s79, 0xe800
	s_cselect_b32 s84, s0, 0
	ds_read_b64_tr_b16 v[76:77], v141 offset:55296
	ds_read_b64_tr_b16 v[78:79], v141 offset:55808
	s_waitcnt lgkmcnt(6)
	v_mfma_f32_32x32x16_bf16 v[16:31], v[128:131], v[68:71], v[16:31]
	v_exp_f32_e32 v56, v56
	v_exp_f32_e32 v57, v57
	v_exp_f32_e32 v58, v58
	v_exp_f32_e32 v59, v59
	s_add_i32 s0, s82, 0x3000
	s_cmpk_lg_u32 s82, 0x9000
	s_cselect_b32 s85, s0, 0
	ds_read_b64_tr_b16 v[68:69], v141 offset:52224
	ds_read_b64_tr_b16 v[70:71], v141 offset:52736
	s_waitcnt lgkmcnt(6)
	v_mfma_f32_32x32x16_bf16 v[0:15], v[128:131], v[72:75], v[0:15]
	v_exp_f32_e32 v60, v60
	v_exp_f32_e32 v61, v61
	v_exp_f32_e32 v62, v62
	v_exp_f32_e32 v63, v63
	s_add_u32 s68, s68, 0x30000
	s_addc_u32 s69, s69, 0
	ds_read_b64_tr_b16 v[72:73], v141 offset:56320
	ds_read_b64_tr_b16 v[74:75], v141 offset:56832
	s_waitcnt lgkmcnt(6)
	v_mfma_f32_32x32x16_bf16 v[16:31], v[124:127], v[64:67], v[16:31]
	v_exp_f32_e32 v32, v32
	v_exp_f32_e32 v33, v33
	v_exp_f32_e32 v34, v34
	v_exp_f32_e32 v35, v35
	s_add_u32 s48, s48, 0x48000
	s_addc_u32 s49, s49, 0
	v_add_u32_e32 v64, s82, v179
	ds_read_b128 v[80:83], v64
	s_waitcnt lgkmcnt(5)
	v_mfma_f32_32x32x16_bf16 v[0:15], v[124:127], v[76:79], v[0:15]
	v_exp_f32_e32 v36, v36
	v_exp_f32_e32 v37, v37
	v_exp_f32_e32 v38, v38
	v_exp_f32_e32 v39, v39
	s_add_u32 s8, s8, 0x2000
	s_addc_u32 s9, s9, 0
	ds_read_b128 v[136:139], v64 offset:512
	s_waitcnt lgkmcnt(4)
	v_mfma_f32_32x32x16_bf16 v[16:31], v[120:123], v[68:71], v[16:31]
	v_exp_f32_e32 v40, v40
	v_exp_f32_e32 v41, v41
	v_exp_f32_e32 v42, v42
	v_exp_f32_e32 v43, v43
	s_add_i32 s0, s87, 2
	ds_read_b128 v[140:143], v64 offset:2048
	s_waitcnt lgkmcnt(3)
	v_mfma_f32_32x32x16_bf16 v[0:15], v[120:123], v[72:75], v[0:15]
	v_exp_f32_e32 v44, v44
	v_exp_f32_e32 v45, v45
	v_exp_f32_e32 v46, v46
	v_exp_f32_e32 v47, v47
	s_cmp_lt_u32 s90, 4
	s_cbranch_scc0 .Lstg_end2
	s_waitcnt vmcnt(3) lgkmcnt(0)
	s_barrier

.LBB0_587:
	s_cmp_ge_u32 s0, s80
	s_cbranch_scc1 .LBB0_597
	s_mov_b32 s87, s0
	s_mov_b32 s0, s86
	s_mov_b32 s86, s84
	s_mov_b32 s84, s83
	s_mov_b32 s83, s85
	s_branch .LBB0_571

.LBB0_684:
	v_add_f32_e32 v48, v92, v93
	v_add_f32_e32 v48, v94, v48
	v_add_f32_e32 v48, v95, v48
	v_add_f32_e32 v48, v96, v48
	v_add_f32_e32 v48, v97, v48
	v_add_f32_e32 v48, v98, v48
	v_add_f32_e32 v48, v99, v48
	v_add_f32_e32 v48, v100, v48
	v_add_f32_e32 v48, v101, v48
	v_add_f32_e32 v48, v102, v48
	v_add_f32_e32 v48, v103, v48
	v_add_f32_e32 v48, v104, v48
	v_add_f32_e32 v48, v105, v48
	v_add_f32_e32 v48, v106, v48
	v_add_f32_e32 v48, v107, v48
	v_add_f32_e32 v48, v48, v32
	v_add_f32_e32 v48, v33, v48
	v_add_f32_e32 v48, v34, v48
	v_add_f32_e32 v48, v35, v48
	v_add_f32_e32 v48, v36, v48
	v_add_f32_e32 v48, v37, v48
	v_add_f32_e32 v48, v38, v48
	v_add_f32_e32 v48, v39, v48
	v_add_f32_e32 v48, v40, v48
	v_add_f32_e32 v48, v41, v48
	v_add_f32_e32 v48, v42, v48
	v_add_f32_e32 v48, v43, v48
	v_add_f32_e32 v48, v44, v48
	v_add_f32_e32 v48, v45, v48
	v_add_f32_e32 v48, v46, v48
	v_add_f32_e32 v48, v47, v48
	v_add_f32_e32 v48, v56, v48
	v_cvt_pk_bf16_f32 v32, v32, v33
	v_cvt_pk_bf16_f32 v50, v92, v93
	v_cvt_pk_bf16_f32 v51, v94, v95
	v_cvt_pk_bf16_f32 v52, v96, v97
	v_cvt_pk_bf16_f32 v53, v98, v99
	v_cvt_pk_bf16_f32 v54, v100, v101
	v_cvt_pk_bf16_f32 v55, v102, v103
	v_cvt_pk_bf16_f32 v56, v104, v105
	v_cvt_pk_bf16_f32 v57, v106, v107
	v_cvt_pk_bf16_f32 v33, v34, v35
	v_cvt_pk_bf16_f32 v34, v36, v37
	v_cvt_pk_bf16_f32 v35, v38, v39
	v_cvt_pk_bf16_f32 v36, v40, v41
	v_cvt_pk_bf16_f32 v37, v42, v43
	v_cvt_pk_bf16_f32 v38, v44, v45
	v_cvt_pk_bf16_f32 v39, v46, v47
	ds_read_b64_tr_b16 v[40:41],v171 offset:0
	ds_read_b64_tr_b16 v[42:43],v171 offset:512
	ds_read_b64_tr_b16 v[44:45],v171 offset:1024
	ds_read_b64_tr_b16 v[46:47],v171 offset:1536
	ds_read_b64_tr_b16 v[58:59],v171 offset:2048
	ds_read_b64_tr_b16 v[60:61],v171 offset:2560
	ds_read_b64_tr_b16 v[62:63],v171 offset:3072
	ds_read_b64_tr_b16 v[64:65],v171 offset:3584
	s_waitcnt lgkmcnt(0)
	s_nop 0
	v_mfma_f32_32x32x16_bf16 v[0:15], v[50:53], v[40:43], v[0:15]
	ds_read_b64_tr_b16 v[40:41],v171 offset:4096
	ds_read_b64_tr_b16 v[42:43],v171 offset:4608
	v_mfma_f32_32x32x16_bf16 v[0:15], v[54:57], v[44:47], v[0:15]
	ds_read_b64_tr_b16 v[44:45],v171 offset:5120
	ds_read_b64_tr_b16 v[46:47],v171 offset:5632
	v_mfma_f32_32x32x16_bf16 v[0:15], v[32:35], v[58:61], v[0:15]
	ds_read_b64_tr_b16 v[58:59],v171 offset:6144
	ds_read_b64_tr_b16 v[60:61],v171 offset:6656
	ds_read_b64_tr_b16 v[66:67],v171 offset:7168
	ds_read_b64_tr_b16 v[68:69],v171 offset:7680
	s_waitcnt lgkmcnt(0)
	v_mfma_f32_32x32x16_bf16 v[0:15], v[36:39], v[62:65], v[0:15]
	v_mfma_f32_32x32x16_bf16 v[16:31], v[50:53], v[40:43], v[16:31]
	v_mfma_f32_32x32x16_bf16 v[16:31], v[54:57], v[44:47], v[16:31]
	v_mfma_f32_32x32x16_bf16 v[16:31], v[32:35], v[58:61], v[16:31]
	v_mov_b32_e32 v32, v48
	s_nop 1
	v_permlane32_swap_b32_e32 v48, v32
	v_mfma_f32_32x32x16_bf16 v[16:31], v[36:39], v[66:69], v[16:31]
	s_mov_b64 s[0:1], exec
	v_readlane_b32 s6, v245, 61
	v_readlane_b32 s7, v245, 62
	s_and_b64 s[6:7], s[0:1], s[6:7]
	s_mov_b64 exec, s[6:7]
	v_add_f32_e32 v32, v48, v32
	ds_write_b32 v172, v32 offset:128
	s_or_b64 exec, exec, s[0:1]
	s_waitcnt lgkmcnt(0)
	ds_read_b128 v[32:35], v145 offset:128
	ds_read_b128 v[36:39], v145 offset:160
	s_lshl_b64 s[0:1], s[4:5], 24
	v_readlane_b32 s4, v246, 45
	s_add_u32 s4, s4, s0
	v_readlane_b32 s5, v246, 46
	s_addc_u32 s5, s5, s1
	s_add_u32 s6, s4, s12
	s_waitcnt lgkmcnt(1)
	v_rcp_f32_e32 v40, v32
	s_addc_u32 s7, s5, 0
	v_readlane_b32 s4, v246, 47
	s_add_u32 s0, s4, s0
	v_readlane_b32 s4, v246, 48
	s_addc_u32 s1, s4, s1
	s_add_u32 s4, s0, s12
	v_rcp_f32_e32 v41, v33
	v_lshlrev_b32_e32 v48, 1, v170
	v_readlane_b32 s0, v245, 63
	v_mul_f32_e32 v0, v0, v40
	v_rcp_f32_e32 v42, v34
	v_add3_u32 v48, s0, v173, v48
	v_cvt_pk_bf16_f32 v0, v0, s0
	ds_write_b16 v48, v0
	v_mul_f32_e32 v0, v16, v40
	v_cvt_pk_bf16_f32 v0, v0, s0
	ds_write_b16 v48, v0 offset:64
	v_mul_f32_e32 v0, v1, v41
	v_cvt_pk_bf16_f32 v0, v0, s0
	ds_write_b16 v48, v0 offset:128
	v_mul_f32_e32 v0, v17, v41
	v_cvt_pk_bf16_f32 v0, v0, s0
	v_rcp_f32_e32 v43, v35
	ds_write_b16 v48, v0 offset:192
	v_mul_f32_e32 v0, v2, v42
	v_cvt_pk_bf16_f32 v0, v0, s0
	ds_write_b16 v48, v0 offset:256
	v_mul_f32_e32 v0, v18, v42
	v_cvt_pk_bf16_f32 v0, v0, s0
	s_waitcnt lgkmcnt(5)
	v_rcp_f32_e32 v44, v36
	ds_write_b16 v48, v0 offset:320
	v_mul_f32_e32 v0, v3, v43
	v_cvt_pk_bf16_f32 v0, v0, s0
	ds_write_b16 v48, v0 offset:384
	v_mul_f32_e32 v0, v19, v43
	v_cvt_pk_bf16_f32 v0, v0, s0
	v_rcp_f32_e32 v45, v37
	ds_write_b16 v48, v0 offset:448
	v_mul_f32_e32 v0, v4, v44
	v_cvt_pk_bf16_f32 v0, v0, s0
	ds_write_b16 v48, v0 offset:1024
	v_mul_f32_e32 v0, v20, v44
	v_cvt_pk_bf16_f32 v0, v0, s0
	v_rcp_f32_e32 v46, v38
	ds_write_b16 v48, v0 offset:1088
	v_mul_f32_e32 v0, v5, v45
	v_cvt_pk_bf16_f32 v0, v0, s0
	ds_write_b16 v48, v0 offset:1152
	v_mul_f32_e32 v0, v21, v45
	ds_read_b128 v[32:35], v145 offset:192
	v_cvt_pk_bf16_f32 v0, v0, s0
	v_rcp_f32_e32 v47, v39
	ds_write_b16 v48, v0 offset:1216
	v_mul_f32_e32 v0, v6, v46
	v_cvt_pk_bf16_f32 v0, v0, s0
	ds_write_b16 v48, v0 offset:1280
	v_mul_f32_e32 v0, v22, v46
	v_cvt_pk_bf16_f32 v0, v0, s0
	ds_read_b128 v[36:39], v145 offset:224
	s_waitcnt lgkmcnt(3)
	v_rcp_f32_e32 v32, v32
	ds_write_b16 v48, v0 offset:1344
	v_mul_f32_e32 v0, v7, v47
	v_cvt_pk_bf16_f32 v0, v0, s0
	ds_write_b16 v48, v0 offset:1408
	v_mul_f32_e32 v0, v23, v47
	v_cvt_pk_bf16_f32 v0, v0, s0
	v_rcp_f32_e32 v33, v33
	ds_write_b16 v48, v0 offset:1472
	v_mul_f32_e32 v0, v8, v32
	v_cvt_pk_bf16_f32 v0, v0, s0
	ds_write_b16 v48, v0 offset:2048
	v_mul_f32_e32 v0, v24, v32
	v_cvt_pk_bf16_f32 v0, v0, s0
	v_rcp_f32_e32 v34, v34
	ds_write_b16 v48, v0 offset:2112
	v_mul_f32_e32 v0, v9, v33
	v_cvt_pk_bf16_f32 v0, v0, s0
	ds_write_b16 v48, v0 offset:2176
	v_mul_f32_e32 v0, v25, v33
	v_cvt_pk_bf16_f32 v0, v0, s0
	v_rcp_f32_e32 v35, v35
	ds_write_b16 v48, v0 offset:2240
	v_mul_f32_e32 v0, v10, v34
	v_cvt_pk_bf16_f32 v0, v0, s0
	ds_write_b16 v48, v0 offset:2304
	v_mul_f32_e32 v0, v26, v34
	v_cvt_pk_bf16_f32 v0, v0, s0
	s_waitcnt lgkmcnt(8)
	v_rcp_f32_e32 v36, v36
	ds_write_b16 v48, v0 offset:2368
	v_mul_f32_e32 v0, v11, v35
	v_cvt_pk_bf16_f32 v0, v0, s0
	ds_write_b16 v48, v0 offset:2432
	v_mul_f32_e32 v0, v27, v35
	v_cvt_pk_bf16_f32 v0, v0, s0
	v_rcp_f32_e32 v37, v37
	ds_write_b16 v48, v0 offset:2496
	v_mul_f32_e32 v0, v12, v36
	v_cvt_pk_bf16_f32 v0, v0, s0
	ds_write_b16 v48, v0 offset:3072
	v_mul_f32_e32 v0, v28, v36
	v_cvt_pk_bf16_f32 v0, v0, s0
	v_rcp_f32_e32 v38, v38
	ds_write_b16 v48, v0 offset:3136
	v_mul_f32_e32 v0, v13, v37
	v_cvt_pk_bf16_f32 v0, v0, s0
	ds_write_b16 v48, v0 offset:3200
	v_mul_f32_e32 v0, v29, v37
	v_cvt_pk_bf16_f32 v0, v0, s0
	v_rcp_f32_e32 v39, v39
	ds_write_b16 v48, v0 offset:3264
	v_mul_f32_e32 v0, v14, v38
	v_cvt_pk_bf16_f32 v0, v0, s0
	ds_write_b16 v48, v0 offset:3328
	v_mul_f32_e32 v0, v30, v38
	v_cvt_pk_bf16_f32 v0, v0, s0
	ds_write_b16 v48, v0 offset:3392
	v_mul_f32_e32 v0, v15, v39
	v_cvt_pk_bf16_f32 v0, v0, s0
	ds_write_b16 v48, v0 offset:3456
	v_mul_f32_e32 v0, v31, v39
	s_addc_u32 s5, s1, 0
	v_cvt_pk_bf16_f32 v0, v0, s0
	s_lshl_b64 s[0:1], s[2:3], 11
	s_add_u32 s2, s6, s0
	s_addc_u32 s3, s7, s1
	v_mov_b32_e32 v145, 0
	ds_write_b16 v48, v0 offset:3520
	v_lshl_add_u64 v[20:21], s[2:3], 0, v[144:145]
	s_waitcnt lgkmcnt(0)
	v_lshl_add_u64 v[0:1], v[20:21], 0, v[140:141]
	global_load_dwordx4 v[0:3], v[0:1], off offset:1536
	v_lshl_add_u64 v[4:5], v[20:21], 0, v[142:143]
	global_load_dwordx4 v[4:7], v[4:5], off offset:1536
	v_lshl_add_u64 v[8:9], v[20:21], 0, v[166:167]
	global_load_dwordx4 v[8:11], v[8:9], off offset:1536
	v_lshl_add_u64 v[20:21], v[20:21], 0, v[168:169]
	global_load_dwordx4 v[20:23], v[20:21], off offset:1536
	ds_read_b128 v[12:15], v177
	ds_read_b128 v[16:19], v176
	s_add_u32 s0, s4, s0
	s_addc_u32 s1, s5, s1
	v_lshl_add_u64 v[24:25], s[0:1], 0, v[144:145]
	s_waitcnt lgkmcnt(1)
	v_lshlrev_b32_e32 v26, 16, v12
	v_and_b32_e32 v27, 0xffff0000, v12
	v_lshlrev_b32_e32 v12, 16, v13
	v_and_b32_e32 v13, 0xffff0000, v13
	s_cmp_gt_i32 s85, 4
	s_waitcnt vmcnt(3)
	v_lshlrev_b32_e32 v28, 16, v0
	v_and_b32_e32 v29, 0xffff0000, v0
	v_pk_mul_f32 v[26:27], v[26:27], v[28:29]
	s_nop 0
	v_cvt_pk_bf16_f32 v0, v26, v27
	v_lshlrev_b32_e32 v26, 16, v1
	v_and_b32_e32 v27, 0xffff0000, v1
	v_pk_mul_f32 v[12:13], v[12:13], v[26:27]
	v_lshlrev_b32_e32 v26, 16, v2
	v_cvt_pk_bf16_f32 v1, v12, v13
	v_lshlrev_b32_e32 v12, 16, v14
	v_and_b32_e32 v13, 0xffff0000, v14
	v_and_b32_e32 v27, 0xffff0000, v2
	v_pk_mul_f32 v[12:13], v[12:13], v[26:27]
	v_lshlrev_b32_e32 v14, 16, v3
	v_cvt_pk_bf16_f32 v2, v12, v13
	v_lshlrev_b32_e32 v12, 16, v15
	v_and_b32_e32 v13, 0xffff0000, v15
	v_and_b32_e32 v15, 0xffff0000, v3
	v_pk_mul_f32 v[12:13], v[12:13], v[14:15]
	s_waitcnt vmcnt(1)
	v_lshlrev_b32_e32 v14, 16, v8
	v_cvt_pk_bf16_f32 v3, v12, v13
	v_lshl_add_u64 v[12:13], v[24:25], 0, v[140:141]
	global_store_dwordx4 v[12:13], v[0:3], off offset:1536 sc1
	v_and_b32_e32 v15, 0xffff0000, v8
	v_lshlrev_b32_e32 v8, 16, v9
	s_waitcnt lgkmcnt(0)
	v_lshlrev_b32_e32 v0, 16, v16
	v_and_b32_e32 v1, 0xffff0000, v16
	v_lshlrev_b32_e32 v2, 16, v4
	v_and_b32_e32 v3, 0xffff0000, v4
	v_pk_mul_f32 v[0:1], v[0:1], v[2:3]
	v_lshlrev_b32_e32 v2, 16, v17
	v_and_b32_e32 v3, 0xffff0000, v17
	v_lshlrev_b32_e32 v4, 16, v5
	v_and_b32_e32 v5, 0xffff0000, v5
	v_pk_mul_f32 v[2:3], v[2:3], v[4:5]
	v_cvt_pk_bf16_f32 v0, v0, v1
	v_cvt_pk_bf16_f32 v1, v2, v3
	v_lshlrev_b32_e32 v2, 16, v18
	v_and_b32_e32 v3, 0xffff0000, v18
	v_lshlrev_b32_e32 v4, 16, v6
	v_and_b32_e32 v5, 0xffff0000, v6
	v_pk_mul_f32 v[2:3], v[2:3], v[4:5]
	v_lshlrev_b32_e32 v4, 16, v19
	v_and_b32_e32 v5, 0xffff0000, v19
	v_lshlrev_b32_e32 v6, 16, v7
	v_and_b32_e32 v7, 0xffff0000, v7
	v_pk_mul_f32 v[12:13], v[4:5], v[6:7]
	ds_read_b128 v[4:7], v175
	v_cvt_pk_bf16_f32 v2, v2, v3
	v_cvt_pk_bf16_f32 v3, v12, v13
	v_lshl_add_u64 v[12:13], v[24:25], 0, v[142:143]
	global_store_dwordx4 v[12:13], v[0:3], off offset:1536 sc1
	ds_read_b128 v[0:3], v174
	s_waitcnt lgkmcnt(1)
	v_lshlrev_b32_e32 v12, 16, v4
	v_and_b32_e32 v13, 0xffff0000, v4
	v_pk_mul_f32 v[12:13], v[12:13], v[14:15]
	v_and_b32_e32 v9, 0xffff0000, v9
	v_cvt_pk_bf16_f32 v4, v12, v13
	v_lshlrev_b32_e32 v12, 16, v5
	v_and_b32_e32 v13, 0xffff0000, v5
	v_pk_mul_f32 v[8:9], v[12:13], v[8:9]
	v_lshlrev_b32_e32 v12, 16, v10
	v_cvt_pk_bf16_f32 v5, v8, v9
	v_lshlrev_b32_e32 v8, 16, v6
	v_and_b32_e32 v9, 0xffff0000, v6
	v_and_b32_e32 v13, 0xffff0000, v10
	v_pk_mul_f32 v[8:9], v[8:9], v[12:13]
	v_lshlrev_b32_e32 v10, 16, v11
	v_cvt_pk_bf16_f32 v6, v8, v9
	v_lshlrev_b32_e32 v8, 16, v7
	v_and_b32_e32 v9, 0xffff0000, v7
	v_and_b32_e32 v11, 0xffff0000, v11
	v_pk_mul_f32 v[8:9], v[8:9], v[10:11]
	s_nop 0
	v_cvt_pk_bf16_f32 v7, v8, v9
	v_lshl_add_u64 v[8:9], v[24:25], 0, v[166:167]
	global_store_dwordx4 v[8:9], v[4:7], off offset:1536 sc1
	s_waitcnt lgkmcnt(0)
	s_nop 0
	v_lshlrev_b32_e32 v4, 16, v0
	v_and_b32_e32 v5, 0xffff0000, v0
	s_waitcnt vmcnt(3)
	v_lshlrev_b32_e32 v6, 16, v20
	v_and_b32_e32 v7, 0xffff0000, v20
	v_pk_mul_f32 v[4:5], v[4:5], v[6:7]
	v_lshlrev_b32_e32 v6, 16, v21
	v_cvt_pk_bf16_f32 v0, v4, v5
	v_lshlrev_b32_e32 v4, 16, v1
	v_and_b32_e32 v5, 0xffff0000, v1
	v_and_b32_e32 v7, 0xffff0000, v21
	v_pk_mul_f32 v[4:5], v[4:5], v[6:7]
	v_lshlrev_b32_e32 v6, 16, v22
	v_cvt_pk_bf16_f32 v1, v4, v5
	v_lshlrev_b32_e32 v4, 16, v2
	v_and_b32_e32 v5, 0xffff0000, v2
	v_and_b32_e32 v7, 0xffff0000, v22
	v_pk_mul_f32 v[4:5], v[4:5], v[6:7]
	v_lshlrev_b32_e32 v6, 16, v23
	v_cvt_pk_bf16_f32 v2, v4, v5
	v_lshlrev_b32_e32 v4, 16, v3
	v_and_b32_e32 v5, 0xffff0000, v3
	v_and_b32_e32 v7, 0xffff0000, v23
	v_pk_mul_f32 v[4:5], v[4:5], v[6:7]
	s_nop 0
	v_cvt_pk_bf16_f32 v3, v4, v5
	v_lshl_add_u64 v[4:5], v[24:25], 0, v[168:169]
	global_store_dwordx4 v[4:5], v[0:3], off offset:1536 sc1
	s_waitcnt lgkmcnt(0)
	s_barrier
	s_cbranch_scc0 .LBB0_742
	s_andn2_b64 vcc, exec, s[88:89]
	s_mov_b64 s[2:3], 0
	s_cbranch_vccnz .LBB0_689
	v_mbcnt_lo_u32_b32 v0, -1, 0
	v_mbcnt_hi_u32_b32 v0, -1, v0
	s_nop 0
	v_cmp_eq_u32_e32 vcc, 0, v0
	s_and_b64 s[2:3], vcc, exec

.LBB0_979:
	s_cmp_lg_u32 0, -1
	s_cselect_b32 s8, 0, 0
	s_add_i32 s8, s8, 0xc000
	v_add_u32_e32 v32, s8, v132
	v_add3_u32 v33, v32, v137, v138
	v_add_f32_e32 v32, v80, v81
	v_add_f32_e32 v32, v82, v32
	v_add_f32_e32 v32, v83, v32
	v_add_f32_e32 v32, v84, v32
	v_add_f32_e32 v32, v85, v32
	v_add_f32_e32 v32, v86, v32
	v_add_f32_e32 v32, v87, v32
	v_add_f32_e32 v32, v88, v32
	v_add_f32_e32 v32, v89, v32
	v_add_f32_e32 v32, v90, v32
	v_add_f32_e32 v32, v91, v32
	v_add_f32_e32 v32, v92, v32
	v_add_f32_e32 v32, v93, v32
	v_add_f32_e32 v32, v94, v32
	v_add_f32_e32 v32, v95, v32
	v_add_f32_e32 v32, v32, v48
	v_add_f32_e32 v32, v49, v32
	v_add_f32_e32 v32, v50, v32
	v_add_f32_e32 v32, v51, v32
	v_add_f32_e32 v32, v52, v32
	v_add_f32_e32 v32, v53, v32
	v_add_f32_e32 v32, v54, v32
	v_add_f32_e32 v32, v55, v32
	v_add_f32_e32 v32, v56, v32
	v_add_f32_e32 v32, v57, v32
	v_add_f32_e32 v32, v58, v32
	v_add_f32_e32 v32, v59, v32
	v_add_f32_e32 v32, v60, v32
	v_add_f32_e32 v32, v61, v32
	v_add_f32_e32 v32, v62, v32
	v_add_f32_e32 v32, v63, v32
	v_add_f32_e32 v32, v40, v32
	v_cvt_pk_bf16_f32 v34, v80, v81
	v_cvt_pk_bf16_f32 v35, v82, v83
	v_cvt_pk_bf16_f32 v36, v84, v85
	v_cvt_pk_bf16_f32 v37, v86, v87
	v_cvt_pk_bf16_f32 v38, v88, v89
	v_cvt_pk_bf16_f32 v39, v90, v91
	v_cvt_pk_bf16_f32 v40, v92, v93
	v_cvt_pk_bf16_f32 v41, v94, v95
	v_cvt_pk_bf16_f32 v42, v48, v49
	v_cvt_pk_bf16_f32 v43, v50, v51
	v_cvt_pk_bf16_f32 v44, v52, v53
	v_cvt_pk_bf16_f32 v45, v54, v55
	v_cvt_pk_bf16_f32 v46, v56, v57
	v_cvt_pk_bf16_f32 v47, v58, v59
	v_cvt_pk_bf16_f32 v48, v60, v61
	v_cvt_pk_bf16_f32 v49, v62, v63
	ds_read_b64_tr_b16 v[50:51],v33 offset:0
	ds_read_b64_tr_b16 v[52:53],v33 offset:512
	ds_read_b64_tr_b16 v[54:55],v33 offset:1024
	ds_read_b64_tr_b16 v[56:57],v33 offset:1536
	ds_read_b64_tr_b16 v[58:59],v33 offset:2048
	ds_read_b64_tr_b16 v[60:61],v33 offset:2560
	ds_read_b64_tr_b16 v[62:63],v33 offset:3072
	ds_read_b64_tr_b16 v[64:65],v33 offset:3584
	s_waitcnt lgkmcnt(0)
	s_nop 0
	v_mfma_f32_32x32x16_bf16 v[0:15], v[34:37], v[50:53], v[0:15]
	ds_read_b64_tr_b16 v[50:51],v33 offset:4096
	ds_read_b64_tr_b16 v[52:53],v33 offset:4608
	v_mfma_f32_32x32x16_bf16 v[0:15], v[38:41], v[54:57], v[0:15]
	ds_read_b64_tr_b16 v[54:55],v33 offset:5120
	ds_read_b64_tr_b16 v[56:57],v33 offset:5632
	v_mfma_f32_32x32x16_bf16 v[0:15], v[42:45], v[58:61], v[0:15]
	ds_read_b64_tr_b16 v[58:59],v33 offset:6144
	ds_read_b64_tr_b16 v[60:61],v33 offset:6656
	ds_read_b64_tr_b16 v[66:67],v33 offset:7168
	ds_read_b64_tr_b16 v[68:69],v33 offset:7680
	s_waitcnt lgkmcnt(0)
	v_mfma_f32_32x32x16_bf16 v[0:15], v[46:49], v[62:65], v[0:15]
	v_mfma_f32_32x32x16_bf16 v[16:31], v[34:37], v[50:53], v[16:31]
	v_mov_b32_e32 v33, v32
	s_nop 1
	v_permlane32_swap_b32_e32 v32, v33
	v_mfma_f32_32x32x16_bf16 v[16:31], v[38:41], v[54:57], v[16:31]
	v_mfma_f32_32x32x16_bf16 v[16:31], v[42:45], v[58:61], v[16:31]
	v_mfma_f32_32x32x16_bf16 v[16:31], v[46:49], v[66:69], v[16:31]
	s_and_saveexec_b64 s[8:9], s[0:1]
	v_add_f32_e32 v32, v32, v33
	v_lshl_add_u32 v33, v184, 2, s15
	ds_write_b32 v33, v32 offset:128
	s_or_b64 exec, exec, s[8:9]
	s_add_u32 s38, s4, 0x3800000
	s_addc_u32 s39, s5, 0
	s_add_u32 s28, s4, 0x700000
	s_addc_u32 s29, s5, 0
	s_waitcnt lgkmcnt(0)
	s_add_u32 s30, s4, 0xf9ff000
	ds_read_b128 v[32:35], v140 offset:128
	ds_read_b128 v[36:39], v140 offset:160
	s_addc_u32 s31, s5, 0
	s_add_u32 s20, s4, 0xf800000
	s_addc_u32 s21, s5, 0
	s_lshl_b64 s[0:1], s[6:7], 24
	s_add_u32 s0, s4, s0
	s_addc_u32 s1, s5, s1
	s_waitcnt lgkmcnt(1)
	v_rcp_f32_e32 v40, v32
	s_add_u32 s4, s0, s14
	s_addc_u32 s1, s1, 0
	s_lshl_b32 s0, s90, 12
	s_add_i32 s0, s0, 0
	v_rcp_f32_e32 v41, v33
	s_add_i32 s0, s0, 0x12800
	v_lshlrev_b32_e32 v48, 9, v136
	v_lshlrev_b32_e32 v49, 1, v135
	v_mul_f32_e32 v0, v0, v40
	v_add3_u32 v48, s0, v48, v49
	v_cvt_pk_bf16_f32 v0, v0, s0
	ds_write_b16 v48, v0
	v_mul_f32_e32 v0, v16, v40
	v_cvt_pk_bf16_f32 v0, v0, s0
	v_rcp_f32_e32 v42, v34
	ds_write_b16 v48, v0 offset:64
	v_mul_f32_e32 v0, v1, v41
	v_cvt_pk_bf16_f32 v0, v0, s0
	ds_write_b16 v48, v0 offset:128
	v_mul_f32_e32 v0, v17, v41
	v_cvt_pk_bf16_f32 v0, v0, s0
	v_rcp_f32_e32 v43, v35
	ds_write_b16 v48, v0 offset:192
	v_mul_f32_e32 v0, v2, v42
	v_cvt_pk_bf16_f32 v0, v0, s0
	ds_write_b16 v48, v0 offset:256
	v_mul_f32_e32 v0, v18, v42
	v_cvt_pk_bf16_f32 v0, v0, s0
	s_waitcnt lgkmcnt(5)
	v_rcp_f32_e32 v44, v36
	ds_write_b16 v48, v0 offset:320
	v_mul_f32_e32 v0, v3, v43
	v_cvt_pk_bf16_f32 v0, v0, s0
	ds_write_b16 v48, v0 offset:384
	v_mul_f32_e32 v0, v19, v43
	v_cvt_pk_bf16_f32 v0, v0, s0
	v_rcp_f32_e32 v45, v37
	ds_write_b16 v48, v0 offset:448
	v_mul_f32_e32 v0, v4, v44
	v_cvt_pk_bf16_f32 v0, v0, s0
	ds_write_b16 v48, v0 offset:1024
	v_mul_f32_e32 v0, v20, v44
	v_cvt_pk_bf16_f32 v0, v0, s0
	v_rcp_f32_e32 v46, v38
	ds_write_b16 v48, v0 offset:1088
	v_mul_f32_e32 v0, v5, v45
	v_cvt_pk_bf16_f32 v0, v0, s0
	ds_write_b16 v48, v0 offset:1152
	v_mul_f32_e32 v0, v21, v45
	ds_read_b128 v[32:35], v140 offset:192
	v_cvt_pk_bf16_f32 v0, v0, s0
	v_rcp_f32_e32 v47, v39
	ds_write_b16 v48, v0 offset:1216
	v_mul_f32_e32 v0, v6, v46
	v_cvt_pk_bf16_f32 v0, v0, s0
	ds_write_b16 v48, v0 offset:1280
	v_mul_f32_e32 v0, v22, v46
	v_cvt_pk_bf16_f32 v0, v0, s0
	ds_read_b128 v[36:39], v140 offset:224
	s_waitcnt lgkmcnt(3)
	v_rcp_f32_e32 v32, v32
	ds_write_b16 v48, v0 offset:1344
	v_mul_f32_e32 v0, v7, v47
	v_cvt_pk_bf16_f32 v0, v0, s0
	ds_write_b16 v48, v0 offset:1408
	v_mul_f32_e32 v0, v23, v47
	v_cvt_pk_bf16_f32 v0, v0, s0
	v_rcp_f32_e32 v33, v33
	ds_write_b16 v48, v0 offset:1472
	v_mul_f32_e32 v0, v8, v32
	v_cvt_pk_bf16_f32 v0, v0, s0
	ds_write_b16 v48, v0 offset:2048
	v_mul_f32_e32 v0, v24, v32
	v_cvt_pk_bf16_f32 v0, v0, s0
	v_rcp_f32_e32 v34, v34
	ds_write_b16 v48, v0 offset:2112
	v_mul_f32_e32 v0, v9, v33
	v_cvt_pk_bf16_f32 v0, v0, s0
	ds_write_b16 v48, v0 offset:2176
	v_mul_f32_e32 v0, v25, v33
	v_cvt_pk_bf16_f32 v0, v0, s0
	v_rcp_f32_e32 v35, v35
	ds_write_b16 v48, v0 offset:2240
	v_mul_f32_e32 v0, v10, v34
	v_cvt_pk_bf16_f32 v0, v0, s0
	ds_write_b16 v48, v0 offset:2304
	v_mul_f32_e32 v0, v26, v34
	v_cvt_pk_bf16_f32 v0, v0, s0
	s_waitcnt lgkmcnt(8)
	v_rcp_f32_e32 v36, v36
	ds_write_b16 v48, v0 offset:2368
	v_mul_f32_e32 v0, v11, v35
	v_cvt_pk_bf16_f32 v0, v0, s0
	ds_write_b16 v48, v0 offset:2432
	v_mul_f32_e32 v0, v27, v35
	v_cvt_pk_bf16_f32 v0, v0, s0
	v_rcp_f32_e32 v37, v37
	ds_write_b16 v48, v0 offset:2496
	v_mul_f32_e32 v0, v12, v36
	v_cvt_pk_bf16_f32 v0, v0, s0
	ds_write_b16 v48, v0 offset:3072
	v_mul_f32_e32 v0, v28, v36
	v_cvt_pk_bf16_f32 v0, v0, s0
	v_rcp_f32_e32 v38, v38
	ds_write_b16 v48, v0 offset:3136
	v_mul_f32_e32 v0, v13, v37
	v_cvt_pk_bf16_f32 v0, v0, s0
	ds_write_b16 v48, v0 offset:3200
	v_mul_f32_e32 v0, v29, v37
	v_cvt_pk_bf16_f32 v0, v0, s0
	v_rcp_f32_e32 v39, v39
	ds_write_b16 v48, v0 offset:3264
	v_mul_f32_e32 v0, v14, v38
	v_cvt_pk_bf16_f32 v0, v0, s0
	ds_write_b16 v48, v0 offset:3328
	v_mul_f32_e32 v0, v30, v38
	v_cvt_pk_bf16_f32 v0, v0, s0
	ds_write_b16 v48, v0 offset:3392
	v_mul_f32_e32 v0, v15, v39
	v_cvt_pk_bf16_f32 v0, v0, s0
	ds_write_b16 v48, v0 offset:3456
	v_mul_f32_e32 v0, v31, v39
	v_cvt_pk_bf16_f32 v0, v0, s0
	s_lshl_b64 s[2:3], s[2:3], 11
	ds_write_b16 v48, v0 offset:3520
	s_add_u32 s2, s4, s2
	v_and_b32_e32 v0, 56, v134
	s_addc_u32 s3, s1, s3
	v_ashrrev_i32_e32 v116, 3, v184
	v_lshlrev_b32_e32 v124, 1, v0
	v_mov_b32_e32 v125, 0
	v_lshl_add_u64 v[16:17], s[2:3], 0, v[124:125]
	s_mov_b64 s[2:3], 0xb000600
	v_ashrrev_i32_e32 v117, 31, v116
	v_lshl_add_u64 v[18:19], v[16:17], 0, s[2:3]
	v_lshlrev_b64 v[20:21], 11, v[116:117]
	s_waitcnt lgkmcnt(0)
	v_lshl_add_u64 v[0:1], v[18:19], 0, v[20:21]
	global_load_dwordx4 v[0:3], v[0:1], off
	v_add_u32_e32 v22, 8, v116
	v_ashrrev_i32_e32 v23, 31, v22
	v_lshlrev_b64 v[24:25], 11, v[22:23]
	v_lshl_add_u64 v[4:5], v[18:19], 0, v[24:25]
	global_load_dwordx4 v[4:7], v[4:5], off
	v_add_u32_e32 v26, 16, v116
	v_ashrrev_i32_e32 v27, 31, v26
	v_lshlrev_b64 v[28:29], 11, v[26:27]
	v_lshl_add_u64 v[8:9], v[18:19], 0, v[28:29]
	v_add_u32_e32 v27, s0, v124
	global_load_dwordx4 v[8:11], v[8:9], off
	v_lshl_add_u32 v12, v116, 7, v27
	ds_read_b128 v[12:15], v12
	s_mov_b64 s[0:1], 0xd800600
	v_lshl_add_u64 v[30:31], v[16:17], 0, s[0:1]
	v_lshl_add_u64 v[20:21], v[30:31], 0, v[20:21]
	s_add_i32 s33, s70, 0
	s_waitcnt lgkmcnt(0)
	v_lshlrev_b32_e32 v16, 16, v12
	v_and_b32_e32 v17, 0xffff0000, v12
	v_lshlrev_b32_e32 v12, 16, v13
	v_and_b32_e32 v13, 0xffff0000, v13
	s_cmpk_gt_u32 s91, 0xff
	s_waitcnt vmcnt(2)
	v_lshlrev_b32_e32 v32, 16, v0
	v_and_b32_e32 v33, 0xffff0000, v0
	v_pk_mul_f32 v[16:17], v[16:17], v[32:33]
	v_add_u32_e32 v32, 24, v116
	v_ashrrev_i32_e32 v33, 31, v32
	v_lshlrev_b64 v[34:35], 11, v[32:33]
	v_cvt_pk_bf16_f32 v0, v16, v17
	v_lshl_add_u64 v[16:17], v[18:19], 0, v[34:35]
	global_load_dwordx4 v[16:19], v[16:17], off
	v_lshlrev_b32_e32 v36, 16, v1
	v_and_b32_e32 v37, 0xffff0000, v1
	v_pk_mul_f32 v[12:13], v[12:13], v[36:37]
	v_lshlrev_b32_e32 v36, 16, v2
	v_cvt_pk_bf16_f32 v1, v12, v13
	v_lshlrev_b32_e32 v12, 16, v14
	v_and_b32_e32 v13, 0xffff0000, v14
	v_and_b32_e32 v37, 0xffff0000, v2
	v_pk_mul_f32 v[12:13], v[12:13], v[36:37]
	v_lshlrev_b32_e32 v38, 16, v3
	v_and_b32_e32 v39, 0xffff0000, v3
	v_lshl_add_u32 v3, v22, 7, v27
	v_cvt_pk_bf16_f32 v2, v12, v13
	v_lshlrev_b32_e32 v36, 16, v15
	v_and_b32_e32 v37, 0xffff0000, v15
	ds_read_b128 v[12:15], v3
	v_pk_mul_f32 v[22:23], v[36:37], v[38:39]
	s_nop 0
	v_cvt_pk_bf16_f32 v3, v22, v23
	global_store_dwordx4 v[20:21], v[0:3], off sc1
	s_waitcnt lgkmcnt(0)
	s_nop 0
	v_lshlrev_b32_e32 v0, 16, v12
	v_and_b32_e32 v1, 0xffff0000, v12
	s_waitcnt vmcnt(3)
	v_lshlrev_b32_e32 v2, 16, v4
	v_and_b32_e32 v3, 0xffff0000, v4
	v_pk_mul_f32 v[0:1], v[0:1], v[2:3]
	v_lshlrev_b32_e32 v2, 16, v13
	v_and_b32_e32 v3, 0xffff0000, v13
	v_lshlrev_b32_e32 v4, 16, v5
	v_and_b32_e32 v5, 0xffff0000, v5
	v_pk_mul_f32 v[2:3], v[2:3], v[4:5]
	v_cvt_pk_bf16_f32 v0, v0, v1
	v_cvt_pk_bf16_f32 v1, v2, v3
	v_lshlrev_b32_e32 v2, 16, v14
	v_and_b32_e32 v3, 0xffff0000, v14
	v_lshlrev_b32_e32 v4, 16, v6
	v_and_b32_e32 v5, 0xffff0000, v6
	v_pk_mul_f32 v[2:3], v[2:3], v[4:5]
	v_lshlrev_b32_e32 v12, 16, v15
	v_cvt_pk_bf16_f32 v2, v2, v3
	v_lshl_add_u32 v3, v26, 7, v27
	v_and_b32_e32 v13, 0xffff0000, v15
	v_lshlrev_b32_e32 v14, 16, v7
	v_and_b32_e32 v15, 0xffff0000, v7
	ds_read_b128 v[4:7], v3
	v_pk_mul_f32 v[12:13], v[12:13], v[14:15]
	s_nop 0
	v_cvt_pk_bf16_f32 v3, v12, v13
	v_lshl_add_u64 v[12:13], v[30:31], 0, v[24:25]
	global_store_dwordx4 v[12:13], v[0:3], off sc1
	s_waitcnt lgkmcnt(0)
	s_nop 0
	v_lshlrev_b32_e32 v0, 16, v4
	v_and_b32_e32 v1, 0xffff0000, v4
	s_waitcnt vmcnt(3)
	v_lshlrev_b32_e32 v2, 16, v8
	v_and_b32_e32 v3, 0xffff0000, v8
	v_pk_mul_f32 v[0:1], v[0:1], v[2:3]
	v_lshlrev_b32_e32 v2, 16, v5
	v_and_b32_e32 v3, 0xffff0000, v5
	v_lshlrev_b32_e32 v4, 16, v9
	v_and_b32_e32 v5, 0xffff0000, v9
	v_pk_mul_f32 v[2:3], v[2:3], v[4:5]
	v_cvt_pk_bf16_f32 v0, v0, v1
	v_cvt_pk_bf16_f32 v1, v2, v3
	v_lshlrev_b32_e32 v2, 16, v6
	v_and_b32_e32 v3, 0xffff0000, v6
	v_lshlrev_b32_e32 v4, 16, v10
	v_and_b32_e32 v5, 0xffff0000, v10
	v_pk_mul_f32 v[2:3], v[2:3], v[4:5]
	v_lshlrev_b32_e32 v8, 16, v7
	v_cvt_pk_bf16_f32 v2, v2, v3
	v_lshl_add_u32 v3, v32, 7, v27
	v_and_b32_e32 v9, 0xffff0000, v7
	ds_read_b128 v[4:7], v3
	v_lshlrev_b32_e32 v10, 16, v11
	v_and_b32_e32 v11, 0xffff0000, v11
	v_pk_mul_f32 v[8:9], v[8:9], v[10:11]
	s_nop 0
	v_cvt_pk_bf16_f32 v3, v8, v9
	v_lshl_add_u64 v[8:9], v[30:31], 0, v[28:29]
	global_store_dwordx4 v[8:9], v[0:3], off sc1
	s_waitcnt lgkmcnt(0)
	s_nop 0
	v_lshlrev_b32_e32 v0, 16, v4
	v_and_b32_e32 v1, 0xffff0000, v4
	s_waitcnt vmcnt(3)
	v_lshlrev_b32_e32 v2, 16, v16
	v_and_b32_e32 v3, 0xffff0000, v16
	v_pk_mul_f32 v[0:1], v[0:1], v[2:3]
	v_lshlrev_b32_e32 v2, 16, v5
	v_and_b32_e32 v3, 0xffff0000, v5
	v_lshlrev_b32_e32 v4, 16, v17
	v_and_b32_e32 v5, 0xffff0000, v17
	v_pk_mul_f32 v[2:3], v[2:3], v[4:5]
	v_cvt_pk_bf16_f32 v0, v0, v1
	v_cvt_pk_bf16_f32 v1, v2, v3
	v_lshlrev_b32_e32 v2, 16, v6
	v_and_b32_e32 v3, 0xffff0000, v6
	v_lshlrev_b32_e32 v4, 16, v18
	v_and_b32_e32 v5, 0xffff0000, v18
	v_pk_mul_f32 v[2:3], v[2:3], v[4:5]
	v_lshlrev_b32_e32 v4, 16, v7
	v_and_b32_e32 v5, 0xffff0000, v7
	v_lshlrev_b32_e32 v6, 16, v19
	v_and_b32_e32 v7, 0xffff0000, v19
	v_pk_mul_f32 v[4:5], v[4:5], v[6:7]
	v_cvt_pk_bf16_f32 v2, v2, v3
	v_cvt_pk_bf16_f32 v3, v4, v5
	v_lshl_add_u64 v[4:5], v[30:31], 0, v[34:35]
	global_store_dwordx4 v[4:5], v[0:3], off sc1
	s_waitcnt lgkmcnt(0)
	s_barrier
	s_barrier
	s_cbranch_scc0 .LBB0_1017
	s_add_i32 s0, s90, -4
	s_mul_i32 s0, s0, s68
	s_add_i32 s0, s0, s94
	s_addk_i32 s0, 0x800
	s_ashr_i32 s1, s0, 31
	s_lshr_b32 s1, s1, 25
	s_add_i32 s1, s0, s1
	s_ashr_i32 s2, s1, 7
	s_and_b32 s1, s1, 0xffffff80
	s_sub_i32 s18, s0, s1
	s_mul_hi_i32 s0, s0, 0x2aaaaaab
	s_lshr_b32 s1, s0, 31
	s_ashr_i32 s0, s0, 8
	s_add_i32 s26, s0, s1
	s_mul_hi_i32 s0, s2, 0x2aaaaaab
	s_lshr_b32 s1, s0, 31
	s_lshr_b32 s0, s0, 1
	s_add_i32 s0, s0, s1
	s_mul_i32 s0, s0, 12
	s_ashr_i32 s27, s26, 31
	s_ashr_i32 s19, s18, 31
	s_lshl_b32 s4, s18, 6
	s_sub_i32 s24, s2, s0
	s_lshl_b64 s[0:1], s[26:27], 13
	s_lshl_b64 s[2:3], s[18:19], 6
	s_sub_i32 s19, 2, s4
	s_add_u32 s0, s0, s2
	s_addc_u32 s1, s1, s3
	s_add_u32 s34, s0, -3
	s_addc_u32 s35, s1, -1
	s_lshl_b32 s22, s24, 6
	s_ashr_i32 s23, s22, 31
	s_lshl_b64 s[0:1], s[22:23], 1
	s_add_u32 s0, s38, s0
	s_addc_u32 s1, s39, s1
	s_movk_i32 s4, 0x43
	v_lshl_add_u64 v[0:1], s[0:1], 0, v[124:125]
	v_cmp_gt_i32_e64 s[0:1], s4, v116
	v_cmp_lt_i32_e32 vcc, s19, v116
	s_and_b64 s[6:7], s[0:1], vcc
	v_mov_b32_e32 v65, v125
	v_mov_b32_e32 v66, v125
	v_mov_b32_e32 v67, v125
	s_and_saveexec_b64 s[2:3], s[6:7]
	s_cbranch_execz .LBB0_984
	v_lshl_add_u64 v[2:3], s[34:35], 0, v[116:117]
	s_movk_i32 s5, 0x600
	v_mad_u64_u32 v[4:5], s[6:7], v2, s5, v[0:1]
	v_mad_i32_i24 v5, v3, s5, v5
	global_load_dwordx4 v[64:67], v[4:5], off
	s_waitcnt vmcnt(0)
	v_mov_b32_e32 v125, v64
